# attention loops: stage next K/V tile into LDS before the second tile's compute instead of at the loop bottom
# speedup vs baseline: 1.0398x; 1.0016x over previous
; #define LAS __attribute__((address_space(3)))
;     __device__ __forceinline__ bool skip(int t) const { const int nb = t >> 2; if (nb >= qb) return 64 * (t & 3) > wq0 + 31; return !__any((int)((sel >> nb) & 1u)); }
; template <bool HAS_POST, class MaskF>
; __device__ __forceinline__ void attn_run(LAS unsigned char* lds, const bf16* Kg, const bf16* Vg, int pitch, int t0, int t1,
;                                          const bf16x8 (&qr)[4], f32x16& o0, f32x16& o1, f32x16& o2, MaskF& mf, const int wv) {
;     ...
;         for (int j = 0; j < 2; ++j) {
;             const int t = ts + j;
;             if (t >= t1) break;
;             if (mf.skip(t)) continue;
;     ...
;         if (more) {
;             *(LAS v4u*)(lds + ((cur ^ 1) * 2) * KBUF + kwoff) = kreg0; *(LAS v4u*)(lds + ((cur ^ 1) * 2) * VBUF + vwoff) = vreg0;
;             if (more2) { *(LAS v4u*)(lds + ((cur ^ 1) * 2 + 1) * KBUF + kwoff) = kreg1; *(LAS v4u*)(lds + ((cur ^ 1) * 2 + 1) * VBUF + vwoff) = vreg1; }
;         }
.LBB0_867:
	s_andn2_b64 vcc, exec, s[14:15]
	s_cbranch_vccnz .Lew_skip_20760
	s_xor_b32 s0, s18, 2
	s_mul_i32 s1, s0, 0x2400
	v_add_u32_e32 v50, s1, v114
	v_lshl_add_u32 v51, s0, 13, v163
	s_and_b64 vcc, exec, s[6:7]
	s_waitcnt vmcnt(1)
	ds_write_b128 v50, v[82:85]
	s_waitcnt vmcnt(0)
	ds_write_b128 v51, v[86:89] offset:36864
	s_mov_b64 s[14:15], 0
	s_cbranch_vccnz .Lew_skip_20760
	ds_write_b128 v50, v[90:93] offset:9216
	ds_write_b128 v51, v[94:97] offset:45056

; #define LAS __attribute__((address_space(3)))
; template <bool HAS_POST, class MaskF>
; __device__ __forceinline__ void attn_run(LAS unsigned char* lds, const bf16* Kg, const bf16* Vg, int pitch, int t0, int t1,
;                                          const bf16x8 (&qr)[4], f32x16& o0, f32x16& o1, f32x16& o2, MaskF& mf, const int wv) {
;     ...
;         if (more) {
;             *(LAS v4u*)(lds + ((cur ^ 1) * 2) * KBUF + kwoff) = kreg0; *(LAS v4u*)(lds + ((cur ^ 1) * 2) * VBUF + vwoff) = vreg0;
;             if (more2) { *(LAS v4u*)(lds + ((cur ^ 1) * 2 + 1) * KBUF + kwoff) = kreg1; *(LAS v4u*)(lds + ((cur ^ 1) * 2 + 1) * VBUF + vwoff) = vreg1; }
;         }
.LBB0_937:
	s_andn2_b64 vcc, exec, s[96:97]
	s_cbranch_vccnz .Lew_skip_22585
	s_xor_b32 s0, s5, 2
	s_mul_i32 s1, s0, 0x2400
	v_add_u32_e32 v50, s1, v161
	v_lshl_add_u32 v51, s0, 13, v162
	s_and_b64 vcc, exec, s[92:93]
	s_waitcnt vmcnt(1)
	ds_write_b128 v50, v[82:85]
	s_waitcnt vmcnt(0)
	ds_write_b128 v51, v[86:89] offset:36864
	s_mov_b64 s[96:97], 0
	s_cbranch_vccnz .Lew_skip_22585
	ds_write_b128 v50, v[90:93] offset:9216
	ds_write_b128 v51, v[94:97] offset:45056

; #define LAS __attribute__((address_space(3)))
; template <bool HAS_POST, class MaskF>
; __device__ __forceinline__ void attn_run(LAS unsigned char* lds, const bf16* Kg, const bf16* Vg, int pitch, int t0, int t1,
;                                          const bf16x8 (&qr)[4], f32x16& o0, f32x16& o1, f32x16& o2, MaskF& mf, const int wv) {
;     ...
;         if (more) {
;             *(LAS v4u*)(lds + ((cur ^ 1) * 2) * KBUF + kwoff) = kreg0; *(LAS v4u*)(lds + ((cur ^ 1) * 2) * VBUF + vwoff) = vreg0;
;             if (more2) { *(LAS v4u*)(lds + ((cur ^ 1) * 2 + 1) * KBUF + kwoff) = kreg1; *(LAS v4u*)(lds + ((cur ^ 1) * 2 + 1) * VBUF + vwoff) = vreg1; }
;         }
.LBB0_979:
	s_andn2_b64 vcc, exec, s[20:21]
	s_cbranch_vccnz .Lew_skip_23466
	s_xor_b32 s0, s97, 2
	s_mul_i32 s1, s0, 0x2400
	v_add_u32_e32 v50, s1, v114
	v_lshl_add_u32 v51, s0, 13, v203
	s_and_b64 vcc, exec, s[94:95]
	s_waitcnt vmcnt(1)
	ds_write_b128 v50, v[132:135]
	s_waitcnt vmcnt(0)
	ds_write_b128 v51, v[136:139] offset:36864
	s_mov_b64 s[20:21], 0
	s_cbranch_vccnz .Lew_skip_23466
	ds_write_b128 v50, v[140:143] offset:9216
	ds_write_b128 v51, v[144:147] offset:45056

; #define LAS __attribute__((address_space(3)))
; template <bool HAS_POST, class MaskF>
; __device__ __forceinline__ void attn_run(LAS unsigned char* lds, const bf16* Kg, const bf16* Vg, int pitch, int t0, int t1,
;                                          const bf16x8 (&qr)[4], f32x16& o0, f32x16& o1, f32x16& o2, MaskF& mf, const int wv) {
;     ...
;         if (more) {
;             *(LAS v4u*)(lds + ((cur ^ 1) * 2) * KBUF + kwoff) = kreg0; *(LAS v4u*)(lds + ((cur ^ 1) * 2) * VBUF + vwoff) = vreg0;
;             if (more2) { *(LAS v4u*)(lds + ((cur ^ 1) * 2 + 1) * KBUF + kwoff) = kreg1; *(LAS v4u*)(lds + ((cur ^ 1) * 2 + 1) * VBUF + vwoff) = vreg1; }
;         }
.LBB0_1194:
	s_andn2_b64 vcc, exec, s[4:5]
	s_cbranch_vccnz .Lew_skip_29169
	s_xor_b32 s0, s59, 2
	s_mul_i32 s1, s0, 0x2400
	v_add_u32_e32 v48, s1, v160
	v_lshl_add_u32 v49, s0, 13, v161
	s_and_b64 vcc, exec, s[6:7]
	s_waitcnt vmcnt(1)
	ds_write_b128 v48, v[96:99]
	s_waitcnt vmcnt(0)
	ds_write_b128 v49, v[100:103] offset:36864
	s_mov_b64 s[4:5], 0
	s_cbranch_vccnz .Lew_skip_29169
	ds_write_b128 v48, v[104:107] offset:9216
	ds_write_b128 v49, v[108:111] offset:45056
